# one static s_setprio 1 for waves 0-3 at kernel entry, no per-segment priority flips
# speedup vs baseline: 1.0012x; 1.0012x over previous
; #define LAS __attribute__((address_space(3)))
; __global__ void __launch_bounds__(512, 2) fwd(Args args) {
;     __shared__ __attribute__((aligned(16))) unsigned char lds_raw[LDS_BYTES];
;     LAS unsigned char* lds = (LAS unsigned char*)lds_raw;
;     volatile LAS unsigned* MISC = (volatile LAS unsigned*)(lds + MISC_OFF);
;     const int tid = threadIdx.x, lane = tid & 63, wave = __builtin_amdgcn_readfirstlane(tid >> 6);
_Z3fwd4Args:
	v_readfirstlane_b32 s32, v0
	s_nop 3
	s_lshr_b32 s32, s32, 8
	s_cmp_eq_u32 s32, 0
	s_cbranch_scc0 .Lprio_done
	s_setprio 1
